# ada GEMV K-loop in P0 rewritten: all loads of a K step in flight, next step prefetched, loop-invariant address registers recomputed after the loop
# speedup vs baseline: 1.0174x; 1.0174x over previous
.LBB0_30:
	v_add_u32_e32 v130, s93, v137
	v_lshlrev_b64 v[248:249], 2, v[130:131]
	v_mad_u64_u32 v[250:251], s[0:1], v130, s69, v[226:227]
	global_load_dwordx3 v[166:168], v[250:251], off nt
	v_add_u32_e32 v132, 1, v130
	v_mad_u64_u32 v[250:251], s[0:1], v132, s69, v[226:227]
	global_load_dwordx3 v[214:216], v[250:251], off nt
	v_add_u32_e32 v132, 2, v130
	v_mad_u64_u32 v[250:251], s[0:1], v132, s69, v[226:227]
	global_load_dwordx3 v[218:220], v[250:251], off nt
	v_add_u32_e32 v132, 3, v130
	v_mad_u64_u32 v[250:251], s[0:1], v132, s69, v[226:227]
	global_load_dwordx3 v[228:230], v[250:251], off nt
	v_add_u32_e32 v132, 4, v130
	v_mad_u64_u32 v[250:251], s[0:1], v132, s69, v[226:227]
	global_load_dwordx3 v[232:234], v[250:251], off nt
	v_add_u32_e32 v132, 5, v130
	v_mad_u64_u32 v[250:251], s[0:1], v132, s69, v[226:227]
	global_load_dwordx3 v[236:238], v[250:251], off nt
	v_add_u32_e32 v132, 6, v130
	v_mad_u64_u32 v[250:251], s[0:1], v132, s69, v[226:227]
	global_load_dwordx3 v[240:242], v[250:251], off nt
	v_add_u32_e32 v132, 7, v130
	v_mad_u64_u32 v[250:251], s[0:1], v132, s69, v[226:227]
	global_load_dwordx3 v[244:246], v[250:251], off nt
	v_lshl_add_u64 v[250:251], v[196:197], 0, v[248:249]
	global_load_dwordx4 v[126:129], v[250:251], off
	global_load_dwordx4 v[138:141], v[250:251], off offset:16
	v_lshl_add_u64 v[250:251], v[198:199], 0, v[248:249]
	global_load_dwordx4 v[142:145], v[250:251], off
	global_load_dwordx4 v[146:149], v[250:251], off offset:16
	v_lshl_add_u64 v[250:251], v[202:203], 0, v[248:249]
	global_load_dwordx4 v[150:153], v[250:251], off
	global_load_dwordx4 v[154:157], v[250:251], off offset:16
	v_lshl_add_u64 v[250:251], v[204:205], 0, v[248:249]
	global_load_dwordx4 v[158:161], v[250:251], off
	global_load_dwordx4 v[162:165], v[250:251], off offset:16
	v_lshl_add_u64 v[250:251], v[206:207], 0, v[248:249]
	global_load_dwordx4 v[172:175], v[250:251], off
	global_load_dwordx4 v[176:179], v[250:251], off offset:16
	v_lshl_add_u64 v[250:251], v[208:209], 0, v[248:249]
	global_load_dwordx4 v[180:183], v[250:251], off
	global_load_dwordx4 v[184:187], v[250:251], off offset:16
	v_lshl_add_u64 v[250:251], v[210:211], 0, v[248:249]
	global_load_dwordx4 v[188:191], v[250:251], off
	global_load_dwordx4 v[192:195], v[250:251], off offset:16
	s_add_i32 s93, s93, 64
	s_waitcnt vmcnt(14)
	v_cvt_pk_bf16_f32 v110, v166, v214
	v_cvt_pk_bf16_f32 v111, v218, v228
	v_cvt_pk_bf16_f32 v112, v232, v236
	v_cvt_pk_bf16_f32 v113, v240, v244
	v_cvt_pk_bf16_f32 v114, v167, v215
	v_cvt_pk_bf16_f32 v115, v219, v229
	v_cvt_pk_bf16_f32 v116, v233, v237
	v_cvt_pk_bf16_f32 v117, v241, v245
	v_cvt_pk_bf16_f32 v118, v168, v216
	v_cvt_pk_bf16_f32 v119, v220, v230
	v_cvt_pk_bf16_f32 v120, v234, v238
	v_cvt_pk_bf16_f32 v121, v242, v246
	v_add_u32_e32 v132, 32, v130
	v_mad_u64_u32 v[250:251], s[0:1], v132, s69, v[226:227]
	global_load_dwordx3 v[166:168], v[250:251], off nt
	v_add_u32_e32 v132, 33, v130
	v_mad_u64_u32 v[250:251], s[0:1], v132, s69, v[226:227]
	global_load_dwordx3 v[214:216], v[250:251], off nt
	v_add_u32_e32 v132, 34, v130
	v_mad_u64_u32 v[250:251], s[0:1], v132, s69, v[226:227]
	global_load_dwordx3 v[218:220], v[250:251], off nt
	v_add_u32_e32 v132, 35, v130
	v_mad_u64_u32 v[250:251], s[0:1], v132, s69, v[226:227]
	global_load_dwordx3 v[228:230], v[250:251], off nt
	v_add_u32_e32 v132, 36, v130
	v_mad_u64_u32 v[250:251], s[0:1], v132, s69, v[226:227]
	global_load_dwordx3 v[232:234], v[250:251], off nt
	v_add_u32_e32 v132, 37, v130
	v_mad_u64_u32 v[250:251], s[0:1], v132, s69, v[226:227]
	global_load_dwordx3 v[236:238], v[250:251], off nt
	v_add_u32_e32 v132, 38, v130
	v_mad_u64_u32 v[250:251], s[0:1], v132, s69, v[226:227]
	global_load_dwordx3 v[240:242], v[250:251], off nt
	v_add_u32_e32 v132, 39, v130
	v_mad_u64_u32 v[250:251], s[0:1], v132, s69, v[226:227]
	global_load_dwordx3 v[244:246], v[250:251], off nt
	s_waitcnt vmcnt(20)
	v_cvt_pk_bf16_f32 v122, v126, v127
	v_cvt_pk_bf16_f32 v123, v128, v129
	v_cvt_pk_bf16_f32 v124, v138, v139
	v_cvt_pk_bf16_f32 v125, v140, v141
	v_lshl_add_u64 v[250:251], v[212:213], 0, v[248:249]
	global_load_dwordx4 v[126:129], v[250:251], off
	global_load_dwordx4 v[138:141], v[250:251], off offset:16
	v_mfma_f32_16x16x32_bf16 v[10:13], v[122:125], v[110:113], v[10:13]
	v_mfma_f32_16x16x32_bf16 v[6:9], v[122:125], v[114:117], v[6:9]
	v_mfma_f32_16x16x32_bf16 v[2:5], v[122:125], v[118:121], v[2:5]
	s_waitcnt vmcnt(20)
	v_cvt_pk_bf16_f32 v122, v142, v143
	v_cvt_pk_bf16_f32 v123, v144, v145
	v_cvt_pk_bf16_f32 v124, v146, v147
	v_cvt_pk_bf16_f32 v125, v148, v149
	v_lshl_add_u64 v[250:251], v[200:201], 0, v[248:249]
	global_load_dwordx4 v[142:145], v[250:251], off
	global_load_dwordx4 v[146:149], v[250:251], off offset:16
	v_mfma_f32_16x16x32_bf16 v[70:73], v[122:125], v[110:113], v[70:73]
	v_mfma_f32_16x16x32_bf16 v[46:49], v[122:125], v[114:117], v[46:49]
	v_mfma_f32_16x16x32_bf16 v[18:21], v[122:125], v[118:121], v[18:21]
	s_waitcnt vmcnt(20)
	v_cvt_pk_bf16_f32 v122, v150, v151
	v_cvt_pk_bf16_f32 v123, v152, v153
	v_cvt_pk_bf16_f32 v124, v154, v155
	v_cvt_pk_bf16_f32 v125, v156, v157
	v_lshl_add_u64 v[250:251], v[196:197], 0, v[248:249]
	global_load_dwordx4 v[150:153], v[250:251], off offset:128
	global_load_dwordx4 v[154:157], v[250:251], off offset:144
	v_mfma_f32_16x16x32_bf16 v[66:69], v[122:125], v[110:113], v[66:69]
	v_mfma_f32_16x16x32_bf16 v[42:45], v[122:125], v[114:117], v[42:45]
	v_mfma_f32_16x16x32_bf16 v[14:17], v[122:125], v[118:121], v[14:17]
	s_waitcnt vmcnt(20)
	v_cvt_pk_bf16_f32 v122, v158, v159
	v_cvt_pk_bf16_f32 v123, v160, v161
	v_cvt_pk_bf16_f32 v124, v162, v163
	v_cvt_pk_bf16_f32 v125, v164, v165
	v_lshl_add_u64 v[250:251], v[198:199], 0, v[248:249]
	global_load_dwordx4 v[158:161], v[250:251], off offset:128
	global_load_dwordx4 v[162:165], v[250:251], off offset:144
	v_mfma_f32_16x16x32_bf16 v[78:81], v[122:125], v[110:113], v[78:81]
	v_mfma_f32_16x16x32_bf16 v[50:53], v[122:125], v[114:117], v[50:53]
	v_mfma_f32_16x16x32_bf16 v[22:25], v[122:125], v[118:121], v[22:25]
	s_waitcnt vmcnt(20)
	v_cvt_pk_bf16_f32 v122, v172, v173
	v_cvt_pk_bf16_f32 v123, v174, v175
	v_cvt_pk_bf16_f32 v124, v176, v177
	v_cvt_pk_bf16_f32 v125, v178, v179
	v_lshl_add_u64 v[250:251], v[202:203], 0, v[248:249]
	global_load_dwordx4 v[172:175], v[250:251], off offset:128
	global_load_dwordx4 v[176:179], v[250:251], off offset:144
	v_mfma_f32_16x16x32_bf16 v[82:85], v[122:125], v[110:113], v[82:85]
	v_mfma_f32_16x16x32_bf16 v[58:61], v[122:125], v[114:117], v[58:61]
	v_mfma_f32_16x16x32_bf16 v[30:33], v[122:125], v[118:121], v[30:33]
	s_waitcnt vmcnt(20)
	v_cvt_pk_bf16_f32 v122, v180, v181
	v_cvt_pk_bf16_f32 v123, v182, v183
	v_cvt_pk_bf16_f32 v124, v184, v185
	v_cvt_pk_bf16_f32 v125, v186, v187
	v_lshl_add_u64 v[250:251], v[204:205], 0, v[248:249]
	global_load_dwordx4 v[180:183], v[250:251], off offset:128
	global_load_dwordx4 v[184:187], v[250:251], off offset:144
	v_mfma_f32_16x16x32_bf16 v[86:89], v[122:125], v[110:113], v[86:89]
	v_mfma_f32_16x16x32_bf16 v[54:57], v[122:125], v[114:117], v[54:57]
	v_mfma_f32_16x16x32_bf16 v[26:29], v[122:125], v[118:121], v[26:29]
	s_waitcnt vmcnt(20)
	v_cvt_pk_bf16_f32 v122, v188, v189
	v_cvt_pk_bf16_f32 v123, v190, v191
	v_cvt_pk_bf16_f32 v124, v192, v193
	v_cvt_pk_bf16_f32 v125, v194, v195
	v_lshl_add_u64 v[250:251], v[206:207], 0, v[248:249]
	global_load_dwordx4 v[188:191], v[250:251], off offset:128
	global_load_dwordx4 v[192:195], v[250:251], off offset:144
	v_mfma_f32_16x16x32_bf16 v[94:97], v[122:125], v[110:113], v[94:97]
	v_mfma_f32_16x16x32_bf16 v[62:65], v[122:125], v[114:117], v[62:65]
	v_mfma_f32_16x16x32_bf16 v[34:37], v[122:125], v[118:121], v[34:37]
	s_waitcnt vmcnt(12)
	v_cvt_pk_bf16_f32 v122, v126, v127
	v_cvt_pk_bf16_f32 v123, v128, v129
	v_cvt_pk_bf16_f32 v124, v138, v139
	v_cvt_pk_bf16_f32 v125, v140, v141
	v_lshl_add_u64 v[250:251], v[208:209], 0, v[248:249]
	global_load_dwordx4 v[126:129], v[250:251], off offset:128
	global_load_dwordx4 v[138:141], v[250:251], off offset:144
	v_mfma_f32_16x16x32_bf16 v[98:101], v[122:125], v[110:113], v[98:101]
	v_mfma_f32_16x16x32_bf16 v[74:77], v[122:125], v[114:117], v[74:77]
	v_mfma_f32_16x16x32_bf16 v[38:41], v[122:125], v[118:121], v[38:41]
	s_waitcnt vmcnt(12)
	v_cvt_pk_bf16_f32 v122, v142, v143
	v_cvt_pk_bf16_f32 v123, v144, v145
	v_cvt_pk_bf16_f32 v124, v146, v147
	v_cvt_pk_bf16_f32 v125, v148, v149
	v_lshl_add_u64 v[250:251], v[210:211], 0, v[248:249]
	global_load_dwordx4 v[142:145], v[250:251], off offset:128
	global_load_dwordx4 v[146:149], v[250:251], off offset:144
	v_mfma_f32_16x16x32_bf16 v[106:109], v[122:125], v[110:113], v[106:109]
	v_mfma_f32_16x16x32_bf16 v[102:105], v[122:125], v[114:117], v[102:105]
	v_mfma_f32_16x16x32_bf16 v[90:93], v[122:125], v[118:121], v[90:93]
	v_cvt_pk_bf16_f32 v110, v166, v214
	v_cvt_pk_bf16_f32 v111, v218, v228
	v_cvt_pk_bf16_f32 v112, v232, v236
	v_cvt_pk_bf16_f32 v113, v240, v244
	v_cvt_pk_bf16_f32 v114, v167, v215
	v_cvt_pk_bf16_f32 v115, v219, v229
	v_cvt_pk_bf16_f32 v116, v233, v237
	v_cvt_pk_bf16_f32 v117, v241, v245
	v_cvt_pk_bf16_f32 v118, v168, v216
	v_cvt_pk_bf16_f32 v119, v220, v230
	v_cvt_pk_bf16_f32 v120, v234, v238
	v_cvt_pk_bf16_f32 v121, v242, v246
	s_waitcnt vmcnt(12)
	v_cvt_pk_bf16_f32 v122, v150, v151
	v_cvt_pk_bf16_f32 v123, v152, v153
	v_cvt_pk_bf16_f32 v124, v154, v155
	v_cvt_pk_bf16_f32 v125, v156, v157
	v_lshl_add_u64 v[250:251], v[212:213], 0, v[248:249]
	global_load_dwordx4 v[150:153], v[250:251], off offset:128
	global_load_dwordx4 v[154:157], v[250:251], off offset:144
	v_mfma_f32_16x16x32_bf16 v[10:13], v[122:125], v[110:113], v[10:13]
	v_mfma_f32_16x16x32_bf16 v[6:9], v[122:125], v[114:117], v[6:9]
	v_mfma_f32_16x16x32_bf16 v[2:5], v[122:125], v[118:121], v[2:5]
	s_waitcnt vmcnt(12)
	v_cvt_pk_bf16_f32 v122, v158, v159
	v_cvt_pk_bf16_f32 v123, v160, v161
	v_cvt_pk_bf16_f32 v124, v162, v163
	v_cvt_pk_bf16_f32 v125, v164, v165
	v_lshl_add_u64 v[250:251], v[200:201], 0, v[248:249]
	global_load_dwordx4 v[158:161], v[250:251], off offset:128
	global_load_dwordx4 v[162:165], v[250:251], off offset:144
	v_mfma_f32_16x16x32_bf16 v[70:73], v[122:125], v[110:113], v[70:73]
	v_mfma_f32_16x16x32_bf16 v[46:49], v[122:125], v[114:117], v[46:49]
	v_mfma_f32_16x16x32_bf16 v[18:21], v[122:125], v[118:121], v[18:21]
	s_waitcnt vmcnt(12)
	v_cvt_pk_bf16_f32 v122, v172, v173
	v_cvt_pk_bf16_f32 v123, v174, v175
	v_cvt_pk_bf16_f32 v124, v176, v177
	v_cvt_pk_bf16_f32 v125, v178, v179
	s_nop 1
	v_mfma_f32_16x16x32_bf16 v[66:69], v[122:125], v[110:113], v[66:69]
	v_mfma_f32_16x16x32_bf16 v[42:45], v[122:125], v[114:117], v[42:45]
	v_mfma_f32_16x16x32_bf16 v[14:17], v[122:125], v[118:121], v[14:17]
	s_waitcnt vmcnt(10)
	v_cvt_pk_bf16_f32 v122, v180, v181
	v_cvt_pk_bf16_f32 v123, v182, v183
	v_cvt_pk_bf16_f32 v124, v184, v185
	v_cvt_pk_bf16_f32 v125, v186, v187
	s_nop 1
	v_mfma_f32_16x16x32_bf16 v[78:81], v[122:125], v[110:113], v[78:81]
	v_mfma_f32_16x16x32_bf16 v[50:53], v[122:125], v[114:117], v[50:53]
	v_mfma_f32_16x16x32_bf16 v[22:25], v[122:125], v[118:121], v[22:25]
	s_waitcnt vmcnt(8)
	v_cvt_pk_bf16_f32 v122, v188, v189
	v_cvt_pk_bf16_f32 v123, v190, v191
	v_cvt_pk_bf16_f32 v124, v192, v193
	v_cvt_pk_bf16_f32 v125, v194, v195
	s_nop 1
	v_mfma_f32_16x16x32_bf16 v[82:85], v[122:125], v[110:113], v[82:85]
	v_mfma_f32_16x16x32_bf16 v[58:61], v[122:125], v[114:117], v[58:61]
	v_mfma_f32_16x16x32_bf16 v[30:33], v[122:125], v[118:121], v[30:33]
	s_waitcnt vmcnt(6)
	v_cvt_pk_bf16_f32 v122, v126, v127
	v_cvt_pk_bf16_f32 v123, v128, v129
	v_cvt_pk_bf16_f32 v124, v138, v139
	v_cvt_pk_bf16_f32 v125, v140, v141
	s_nop 1
	v_mfma_f32_16x16x32_bf16 v[86:89], v[122:125], v[110:113], v[86:89]
	v_mfma_f32_16x16x32_bf16 v[54:57], v[122:125], v[114:117], v[54:57]
	v_mfma_f32_16x16x32_bf16 v[26:29], v[122:125], v[118:121], v[26:29]
	s_waitcnt vmcnt(4)
	v_cvt_pk_bf16_f32 v122, v142, v143
	v_cvt_pk_bf16_f32 v123, v144, v145
	v_cvt_pk_bf16_f32 v124, v146, v147
	v_cvt_pk_bf16_f32 v125, v148, v149
	s_nop 1
	v_mfma_f32_16x16x32_bf16 v[94:97], v[122:125], v[110:113], v[94:97]
	v_mfma_f32_16x16x32_bf16 v[62:65], v[122:125], v[114:117], v[62:65]
	v_mfma_f32_16x16x32_bf16 v[34:37], v[122:125], v[118:121], v[34:37]
	s_waitcnt vmcnt(2)
	v_cvt_pk_bf16_f32 v122, v150, v151
	v_cvt_pk_bf16_f32 v123, v152, v153
	v_cvt_pk_bf16_f32 v124, v154, v155
	v_cvt_pk_bf16_f32 v125, v156, v157
	s_nop 1
	v_mfma_f32_16x16x32_bf16 v[98:101], v[122:125], v[110:113], v[98:101]
	v_mfma_f32_16x16x32_bf16 v[74:77], v[122:125], v[114:117], v[74:77]
	v_mfma_f32_16x16x32_bf16 v[38:41], v[122:125], v[118:121], v[38:41]
	s_waitcnt vmcnt(0)
	v_cvt_pk_bf16_f32 v122, v158, v159
	v_cvt_pk_bf16_f32 v123, v160, v161
	v_cvt_pk_bf16_f32 v124, v162, v163
	v_cvt_pk_bf16_f32 v125, v164, v165
	s_nop 1
	v_mfma_f32_16x16x32_bf16 v[106:109], v[122:125], v[110:113], v[106:109]
	v_mfma_f32_16x16x32_bf16 v[102:105], v[122:125], v[114:117], v[102:105]
	v_mfma_f32_16x16x32_bf16 v[90:93], v[122:125], v[118:121], v[90:93]
	s_cmpk_eq_i32 s93, 0x100
	s_cbranch_scc0 .LBB0_30
	v_lshrrev_b32_e32 v110, 4, v170
	v_lshlrev_b32_e32 v111, 16, v110
	v_lshlrev_b32_e32 v112, 2, v110
	v_or_b32_e32 v112, 0x82, v112
	v_lshlrev_b32_e32 v113, 2, v110
	v_or_b32_e32 v113, 0x80, v113
	v_lshlrev_b32_e32 v114, 2, v110
	v_or_b32_e32 v114, 0x81, v114
	v_or_b32_e32 v132, 0x4000, v111
	v_or_b32_e32 v134, 0x8000, v111
	v_or_b32_e32 v136, 0xc000, v111
	v_or_b32_e32 v138, 0x40000, v111
	v_or_b32_e32 v140, 0x44000, v111
	v_or_b32_e32 v142, 0x48000, v111
	v_or_b32_e32 v144, 0x4c000, v111
	v_or_b32_e32 v146, 0x80000, v111
	v_or_b32_e32 v148, 0x84000, v111
	v_or_b32_e32 v150, 0x88000, v111
	v_or_b32_e32 v152, 0x8c000, v111
	v_or_b32_e32 v154, 0xc0000, v111
	v_or_b32_e32 v156, 0xc4000, v111
	v_or_b32_e32 v158, 0xc8000, v111
	v_or_b32_e32 v160, 0xcc000, v111
	v_or_b32_e32 v162, 0x100000, v111
	v_or_b32_e32 v164, 0x104000, v111
	v_or_b32_e32 v166, 0x108000, v111
	v_or_b32_e32 v168, 0x10c000, v111
	v_or_b32_e32 v172, 0x140000, v111
	v_or_b32_e32 v174, 0x144000, v111
	v_or_b32_e32 v176, 0x148000, v111
	v_or_b32_e32 v178, 0x14c000, v111
	v_or_b32_e32 v180, 0x180000, v111
	v_or_b32_e32 v182, 0x184000, v111
	v_or_b32_e32 v184, 0x188000, v111
	v_or_b32_e32 v186, 0x18c000, v111
	v_or_b32_e32 v188, 0x1c0000, v111
	v_or_b32_e32 v190, 0x1c4000, v111
	v_or_b32_e32 v192, 0x1c8000, v111
	v_or_b32_e32 v194, 0x1cc000, v111
	v_lshlrev_b32_e32 v214, 2, v111
	v_add_u32_e32 v173, 0xffff7100, v135
	v_add_u32_e32 v175, 0xffff7200, v135
	v_add_u32_e32 v177, 0xffff7300, v135
	v_add_u32_e32 v179, 0xffff7400, v135
	v_add_u32_e32 v181, 0xffff7500, v135
	v_add_u32_e32 v183, 0xffff7600, v135
	v_add_u32_e32 v185, 0xffff7700, v135
	v_add_u32_e32 v187, 0xffff7800, v135
	v_add_u32_e32 v189, 0xffff7900, v135
	v_add_u32_e32 v191, 0xffff7a00, v135
	v_add_u32_e32 v193, 0xffff7b00, v135
	v_add_u32_e32 v195, 0xffff7c00, v135
	v_add_u32_e32 v217, 0xffff7d00, v135
	v_add_u32_e32 v219, 0xffff7e00, v135
	v_add_u32_e32 v221, 0xffff7f00, v135
	v_add_u32_e32 v171, 0xffff8000, v135
	v_add_u32_e32 v251, 0xffff8100, v135
	v_add_u32_e32 v252, 0xffff8200, v135
	v_add_u32_e32 v253, 0xffff8300, v135
	v_add_u32_e32 v254, 0xffff8400, v135
	v_add_u32_e32 v139, 0xffff8500, v135
	v_add_u32_e32 v141, 0xffff8600, v135
	v_add_u32_e32 v143, 0xffff8700, v135
	v_add_u32_e32 v145, 0xffff8800, v135
	v_add_u32_e32 v147, 0xffff8900, v135
	v_add_u32_e32 v149, 0xffff8a00, v135
	v_add_u32_e32 v151, 0xffff8b00, v135
	v_add_u32_e32 v153, 0xffff8c00, v135
	v_add_u32_e32 v155, 0xffff8d00, v135
	v_add_u32_e32 v157, 0xffff8e00, v135
	v_add_u32_e32 v159, 0xffff8f00, v135
	v_add_u32_e32 v161, 0xffff9000, v135
	v_add_u32_e32 v163, 0xffff9100, v135
	v_add_u32_e32 v165, 0xffff9200, v135
	v_add_u32_e32 v167, 0xffff9300, v135
	v_lshlrev_b32_e32 v216, 14, v113
	v_lshlrev_b32_e32 v218, 14, v114
	v_lshlrev_b32_e32 v220, 14, v112
	s_and_b64 vcc, exec, s[10:11]
	s_cbranch_vccz .LBB0_33
	v_add_u32_e32 v110, 0xfffe5000, v135
	ds_write_b32 v110, v10
	v_add_u32_e32 v110, 0xfffe5100, v135
	ds_write_b32 v110, v11
	v_add_u32_e32 v110, 0xfffe5200, v135
	ds_write_b32 v110, v12
	v_add_u32_e32 v110, 0xfffe5300, v135
	ds_write_b32 v110, v13
	v_add_u32_e32 v110, 0xfffe5400, v135
	ds_write_b32 v110, v6
	v_add_u32_e32 v110, 0xfffe5500, v135
	ds_write_b32 v110, v7
	v_add_u32_e32 v110, 0xfffe5600, v135
	ds_write_b32 v110, v8
	v_add_u32_e32 v110, 0xfffe5700, v135
	ds_write_b32 v110, v9
	v_add_u32_e32 v110, 0xfffe5800, v135
	ds_write_b32 v110, v2
	v_add_u32_e32 v110, 0xfffe5900, v135
	ds_write_b32 v110, v3
	v_add_u32_e32 v110, 0xfffe5a00, v135
	ds_write_b32 v110, v4
	v_add_u32_e32 v110, 0xfffe5b00, v135
	ds_write_b32 v110, v5
	v_add_u32_e32 v110, 0xfffe5c00, v135
	ds_write_b32 v110, v70
	v_add_u32_e32 v110, 0xfffe5d00, v135
	ds_write_b32 v110, v71
	v_add_u32_e32 v110, 0xfffe5e00, v135
	ds_write_b32 v110, v72
	v_add_u32_e32 v110, 0xfffe5f00, v135
	ds_write_b32 v110, v73
	v_add_u32_e32 v110, 0xfffe6000, v135
	ds_write_b32 v110, v46
	v_add_u32_e32 v110, 0xfffe6100, v135
	ds_write_b32 v110, v47
	v_add_u32_e32 v110, 0xfffe6200, v135
	ds_write_b32 v110, v48
	v_add_u32_e32 v110, 0xfffe6300, v135
	ds_write_b32 v110, v49
	v_add_u32_e32 v110, 0xfffe6400, v135
	ds_write_b32 v110, v18
	v_add_u32_e32 v110, 0xfffe6500, v135
	ds_write_b32 v110, v19
	v_add_u32_e32 v110, 0xfffe6600, v135
	ds_write_b32 v110, v20
	v_add_u32_e32 v110, 0xfffe6700, v135
	ds_write_b32 v110, v21
	v_add_u32_e32 v110, 0xfffe6800, v135
	ds_write_b32 v110, v66
	v_add_u32_e32 v110, 0xfffe6900, v135
	ds_write_b32 v110, v67
	v_add_u32_e32 v110, 0xfffe6a00, v135
	ds_write_b32 v110, v68
	v_add_u32_e32 v110, 0xfffe6b00, v135
	ds_write_b32 v110, v69
	v_add_u32_e32 v110, 0xfffe6c00, v135
	ds_write_b32 v110, v42
	v_add_u32_e32 v110, 0xfffe6d00, v135
	ds_write_b32 v110, v43
	v_add_u32_e32 v110, 0xfffe6e00, v135
	ds_write_b32 v110, v44
	v_add_u32_e32 v110, 0xfffe6f00, v135
	ds_write_b32 v110, v45
	v_add_u32_e32 v110, 0xfffe7000, v135
	ds_write_b32 v110, v14
	v_add_u32_e32 v110, 0xfffe7100, v135
	ds_write_b32 v110, v15
	v_add_u32_e32 v110, 0xfffe7200, v135
	ds_write_b32 v110, v16
	v_add_u32_e32 v110, 0xfffe7300, v135
	ds_write_b32 v110, v17
	v_add_u32_e32 v110, 0xfffe7400, v135
	ds_write_b32 v110, v78
	v_add_u32_e32 v110, 0xfffe7500, v135
	ds_write_b32 v110, v79
	v_add_u32_e32 v110, 0xfffe7600, v135
	ds_write_b32 v110, v80
	v_add_u32_e32 v110, 0xfffe7700, v135
	ds_write_b32 v110, v81
	v_add_u32_e32 v110, 0xfffe7800, v135
	ds_write_b32 v110, v50
	v_add_u32_e32 v110, 0xfffe7900, v135
	ds_write_b32 v110, v51
	v_add_u32_e32 v110, 0xfffe7a00, v135
	ds_write_b32 v110, v52
	v_add_u32_e32 v110, 0xfffe7b00, v135
	ds_write_b32 v110, v53
	v_add_u32_e32 v110, 0xfffe7c00, v135
	ds_write_b32 v110, v22
	v_add_u32_e32 v110, 0xfffe7d00, v135
	ds_write_b32 v110, v23
	v_add_u32_e32 v110, 0xfffe7e00, v135
	ds_write_b32 v110, v24
	v_add_u32_e32 v110, 0xfffe7f00, v135
	ds_write_b32 v110, v25
	v_add_u32_e32 v110, 0xfffe8000, v135
	ds_write_b32 v110, v82
	v_add_u32_e32 v110, 0xfffe8100, v135
	ds_write_b32 v110, v83
	v_add_u32_e32 v110, 0xfffe8200, v135
	ds_write_b32 v110, v84
	v_add_u32_e32 v110, 0xfffe8300, v135
	ds_write_b32 v110, v85
	v_add_u32_e32 v110, 0xfffe8400, v135
	ds_write_b32 v110, v58
	v_add_u32_e32 v110, 0xfffe8500, v135
	ds_write_b32 v110, v59
	v_add_u32_e32 v110, 0xfffe8600, v135
	ds_write_b32 v110, v60
	v_add_u32_e32 v110, 0xfffe8700, v135
	ds_write_b32 v110, v61
	v_add_u32_e32 v110, 0xfffe8800, v135
	ds_write_b32 v110, v30
	v_add_u32_e32 v110, 0xfffe8900, v135
	ds_write_b32 v110, v31
	v_add_u32_e32 v110, 0xfffe8a00, v135
	ds_write_b32 v110, v32
	v_add_u32_e32 v110, 0xfffe8b00, v135
	ds_write_b32 v110, v33
	v_add_u32_e32 v110, 0xfffe8c00, v135
	ds_write_b32 v110, v86
	v_add_u32_e32 v110, 0xfffe8d00, v135
	ds_write_b32 v110, v87
	v_add_u32_e32 v110, 0xfffe8e00, v135
	ds_write_b32 v110, v88
	v_add_u32_e32 v110, 0xfffe8f00, v135
	ds_write_b32 v110, v89
	v_add_u32_e32 v110, 0xfffe9000, v135
	ds_write_b32 v110, v54
	v_add_u32_e32 v110, 0xfffe9100, v135
	ds_write_b32 v110, v55
	v_add_u32_e32 v110, 0xfffe9200, v135
	ds_write_b32 v110, v56
	v_add_u32_e32 v110, 0xfffe9300, v135
	ds_write_b32 v110, v57
	v_add_u32_e32 v110, 0xfffe9400, v135
	ds_write_b32 v110, v26
	v_add_u32_e32 v110, 0xfffe9500, v135
	ds_write_b32 v110, v27
	v_add_u32_e32 v110, 0xfffe9600, v135
	ds_write_b32 v110, v28
	v_add_u32_e32 v110, 0xfffe9700, v135
	ds_write_b32 v110, v29
	v_add_u32_e32 v110, 0xfffe9800, v135
	ds_write_b32 v110, v94
	v_add_u32_e32 v110, 0xfffe9900, v135
	ds_write_b32 v110, v95
	v_add_u32_e32 v110, 0xfffe9a00, v135
	ds_write_b32 v110, v96
	v_add_u32_e32 v110, 0xfffe9b00, v135
	ds_write_b32 v110, v97
	v_add_u32_e32 v110, 0xfffe9c00, v135
	ds_write_b32 v110, v62
	v_add_u32_e32 v110, 0xfffe9d00, v135
	ds_write_b32 v110, v63
	v_add_u32_e32 v110, 0xfffe9e00, v135
	ds_write_b32 v110, v64
	v_add_u32_e32 v110, 0xfffe9f00, v135
	ds_write_b32 v110, v65
	v_add_u32_e32 v110, 0xfffea000, v135
	ds_write_b32 v110, v34
	v_add_u32_e32 v110, 0xfffea100, v135
	ds_write_b32 v110, v35
	v_add_u32_e32 v110, 0xfffea200, v135
	ds_write_b32 v110, v36
	v_add_u32_e32 v110, 0xfffea300, v135
	ds_write_b32 v110, v37
	v_add_u32_e32 v110, 0xfffea400, v135
	ds_write_b32 v110, v98
	v_add_u32_e32 v110, 0xfffea500, v135
	ds_write_b32 v110, v99
	v_add_u32_e32 v110, 0xfffea600, v135
	ds_write_b32 v110, v100
	v_add_u32_e32 v110, 0xfffea700, v135
	ds_write_b32 v110, v101
	v_add_u32_e32 v110, 0xfffea800, v135
	ds_write_b32 v110, v74
	v_add_u32_e32 v110, 0xfffea900, v135
	ds_write_b32 v110, v75
	v_add_u32_e32 v110, 0xfffeaa00, v135
	ds_write_b32 v110, v76
	v_add_u32_e32 v110, 0xfffeab00, v135
	ds_write_b32 v110, v77
	v_add_u32_e32 v110, 0xfffeac00, v135
	ds_write_b32 v110, v38
	v_add_u32_e32 v110, 0xfffead00, v135
	ds_write_b32 v110, v39
	v_add_u32_e32 v110, 0xfffeae00, v135
	ds_write_b32 v110, v40
	v_add_u32_e32 v110, 0xfffeaf00, v135
	ds_write_b32 v110, v41
	v_add_u32_e32 v110, 0xfffeb000, v135
	ds_write_b32 v110, v106
	v_add_u32_e32 v110, 0xfffeb100, v135
	ds_write_b32 v110, v107
	v_add_u32_e32 v110, 0xfffeb200, v135
	ds_write_b32 v110, v108
	v_add_u32_e32 v110, 0xfffeb300, v135
	ds_write_b32 v110, v109
	v_add_u32_e32 v110, 0xfffeb400, v135
	ds_write_b32 v110, v102
	v_add_u32_e32 v110, 0xfffeb500, v135
	ds_write_b32 v110, v103
	v_add_u32_e32 v110, 0xfffeb600, v135
	ds_write_b32 v110, v104
	v_add_u32_e32 v110, 0xfffeb700, v135
	ds_write_b32 v110, v105
	v_add_u32_e32 v110, 0xfffeb800, v135
	ds_write_b32 v110, v90
	v_add_u32_e32 v110, 0xfffeb900, v135
	ds_write_b32 v110, v91
	v_add_u32_e32 v110, 0xfffeba00, v135
	ds_write_b32 v110, v92
	v_add_u32_e32 v110, 0xfffebb00, v135
	ds_write_b32 v110, v93

.LBB0_82:
	v_add_u32_e32 v130, s63, v133
	v_lshlrev_b64 v[248:249], 2, v[130:131]
	v_mad_u64_u32 v[250:251], s[0:1], v130, s69, v[226:227]
	global_load_dwordx3 v[158:160], v[250:251], off nt
	v_add_u32_e32 v132, 1, v130
	v_mad_u64_u32 v[250:251], s[0:1], v132, s69, v[226:227]
	global_load_dwordx3 v[214:216], v[250:251], off nt
	v_add_u32_e32 v132, 2, v130
	v_mad_u64_u32 v[250:251], s[0:1], v132, s69, v[226:227]
	global_load_dwordx3 v[218:220], v[250:251], off nt
	v_add_u32_e32 v132, 3, v130
	v_mad_u64_u32 v[250:251], s[0:1], v132, s69, v[226:227]
	global_load_dwordx3 v[228:230], v[250:251], off nt
	v_add_u32_e32 v132, 4, v130
	v_mad_u64_u32 v[250:251], s[0:1], v132, s69, v[226:227]
	global_load_dwordx3 v[232:234], v[250:251], off nt
	v_add_u32_e32 v132, 5, v130
	v_mad_u64_u32 v[250:251], s[0:1], v132, s69, v[226:227]
	global_load_dwordx3 v[236:238], v[250:251], off nt
	v_add_u32_e32 v132, 6, v130
	v_mad_u64_u32 v[250:251], s[0:1], v132, s69, v[226:227]
	global_load_dwordx3 v[240:242], v[250:251], off nt
	v_add_u32_e32 v132, 7, v130
	v_mad_u64_u32 v[250:251], s[0:1], v132, s69, v[226:227]
	global_load_dwordx3 v[244:246], v[250:251], off nt
	v_lshl_add_u64 v[250:251], v[162:163], 0, v[248:249]
	global_load_dwordx4 v[126:129], v[250:251], off
	global_load_dwordx4 v[138:141], v[250:251], off offset:16
	v_lshl_add_u64 v[250:251], v[164:165], 0, v[248:249]
	global_load_dwordx4 v[142:145], v[250:251], off
	global_load_dwordx4 v[146:149], v[250:251], off offset:16
	v_lshl_add_u64 v[250:251], v[168:169], 0, v[248:249]
	global_load_dwordx4 v[150:153], v[250:251], off
	global_load_dwordx4 v[154:157], v[250:251], off offset:16
	v_lshl_add_u64 v[250:251], v[172:173], 0, v[248:249]
	global_load_dwordx4 v[182:185], v[250:251], off
	global_load_dwordx4 v[186:189], v[250:251], off offset:16
	v_lshl_add_u64 v[250:251], v[174:175], 0, v[248:249]
	global_load_dwordx4 v[190:193], v[250:251], off
	global_load_dwordx4 v[194:197], v[250:251], off offset:16
	v_lshl_add_u64 v[250:251], v[176:177], 0, v[248:249]
	global_load_dwordx4 v[198:201], v[250:251], off
	global_load_dwordx4 v[202:205], v[250:251], off offset:16
	v_lshl_add_u64 v[250:251], v[178:179], 0, v[248:249]
	global_load_dwordx4 v[206:209], v[250:251], off
	global_load_dwordx4 v[210:213], v[250:251], off offset:16
	s_add_i32 s63, s63, 64
	s_waitcnt vmcnt(14)
	v_cvt_pk_bf16_f32 v110, v158, v214
	v_cvt_pk_bf16_f32 v111, v218, v228
	v_cvt_pk_bf16_f32 v112, v232, v236
	v_cvt_pk_bf16_f32 v113, v240, v244
	v_cvt_pk_bf16_f32 v114, v159, v215
	v_cvt_pk_bf16_f32 v115, v219, v229
	v_cvt_pk_bf16_f32 v116, v233, v237
	v_cvt_pk_bf16_f32 v117, v241, v245
	v_cvt_pk_bf16_f32 v118, v160, v216
	v_cvt_pk_bf16_f32 v119, v220, v230
	v_cvt_pk_bf16_f32 v120, v234, v238
	v_cvt_pk_bf16_f32 v121, v242, v246
	v_add_u32_e32 v132, 32, v130
	v_mad_u64_u32 v[250:251], s[0:1], v132, s69, v[226:227]
	global_load_dwordx3 v[158:160], v[250:251], off nt
	v_add_u32_e32 v132, 33, v130
	v_mad_u64_u32 v[250:251], s[0:1], v132, s69, v[226:227]
	global_load_dwordx3 v[214:216], v[250:251], off nt
	v_add_u32_e32 v132, 34, v130
	v_mad_u64_u32 v[250:251], s[0:1], v132, s69, v[226:227]
	global_load_dwordx3 v[218:220], v[250:251], off nt
	v_add_u32_e32 v132, 35, v130
	v_mad_u64_u32 v[250:251], s[0:1], v132, s69, v[226:227]
	global_load_dwordx3 v[228:230], v[250:251], off nt
	v_add_u32_e32 v132, 36, v130
	v_mad_u64_u32 v[250:251], s[0:1], v132, s69, v[226:227]
	global_load_dwordx3 v[232:234], v[250:251], off nt
	v_add_u32_e32 v132, 37, v130
	v_mad_u64_u32 v[250:251], s[0:1], v132, s69, v[226:227]
	global_load_dwordx3 v[236:238], v[250:251], off nt
	v_add_u32_e32 v132, 38, v130
	v_mad_u64_u32 v[250:251], s[0:1], v132, s69, v[226:227]
	global_load_dwordx3 v[240:242], v[250:251], off nt
	v_add_u32_e32 v132, 39, v130
	v_mad_u64_u32 v[250:251], s[0:1], v132, s69, v[226:227]
	global_load_dwordx3 v[244:246], v[250:251], off nt
	s_waitcnt vmcnt(20)
	v_cvt_pk_bf16_f32 v122, v126, v127
	v_cvt_pk_bf16_f32 v123, v128, v129
	v_cvt_pk_bf16_f32 v124, v138, v139
	v_cvt_pk_bf16_f32 v125, v140, v141
	v_lshl_add_u64 v[250:251], v[180:181], 0, v[248:249]
	global_load_dwordx4 v[126:129], v[250:251], off
	global_load_dwordx4 v[138:141], v[250:251], off offset:16
	v_mfma_f32_16x16x32_bf16 v[18:21], v[122:125], v[110:113], v[18:21]
	v_mfma_f32_16x16x32_bf16 v[6:9], v[122:125], v[114:117], v[6:9]
	v_mfma_f32_16x16x32_bf16 v[2:5], v[122:125], v[118:121], v[2:5]
	s_waitcnt vmcnt(20)
	v_cvt_pk_bf16_f32 v122, v142, v143
	v_cvt_pk_bf16_f32 v123, v144, v145
	v_cvt_pk_bf16_f32 v124, v146, v147
	v_cvt_pk_bf16_f32 v125, v148, v149
	v_lshl_add_u64 v[250:251], v[166:167], 0, v[248:249]
	global_load_dwordx4 v[142:145], v[250:251], off
	global_load_dwordx4 v[146:149], v[250:251], off offset:16
	v_mfma_f32_16x16x32_bf16 v[70:73], v[122:125], v[110:113], v[70:73]
	v_mfma_f32_16x16x32_bf16 v[46:49], v[122:125], v[114:117], v[46:49]
	v_mfma_f32_16x16x32_bf16 v[10:13], v[122:125], v[118:121], v[10:13]
	s_waitcnt vmcnt(20)
	v_cvt_pk_bf16_f32 v122, v150, v151
	v_cvt_pk_bf16_f32 v123, v152, v153
	v_cvt_pk_bf16_f32 v124, v154, v155
	v_cvt_pk_bf16_f32 v125, v156, v157
	v_lshl_add_u64 v[250:251], v[162:163], 0, v[248:249]
	global_load_dwordx4 v[150:153], v[250:251], off offset:128
	global_load_dwordx4 v[154:157], v[250:251], off offset:144
	v_mfma_f32_16x16x32_bf16 v[66:69], v[122:125], v[110:113], v[66:69]
	v_mfma_f32_16x16x32_bf16 v[38:41], v[122:125], v[114:117], v[38:41]
	v_mfma_f32_16x16x32_bf16 v[14:17], v[122:125], v[118:121], v[14:17]
	s_waitcnt vmcnt(20)
	v_cvt_pk_bf16_f32 v122, v182, v183
	v_cvt_pk_bf16_f32 v123, v184, v185
	v_cvt_pk_bf16_f32 v124, v186, v187
	v_cvt_pk_bf16_f32 v125, v188, v189
	v_lshl_add_u64 v[250:251], v[164:165], 0, v[248:249]
	global_load_dwordx4 v[182:185], v[250:251], off offset:128
	global_load_dwordx4 v[186:189], v[250:251], off offset:144
	v_mfma_f32_16x16x32_bf16 v[78:81], v[122:125], v[110:113], v[78:81]
	v_mfma_f32_16x16x32_bf16 v[50:53], v[122:125], v[114:117], v[50:53]
	v_mfma_f32_16x16x32_bf16 v[22:25], v[122:125], v[118:121], v[22:25]
	s_waitcnt vmcnt(20)
	v_cvt_pk_bf16_f32 v122, v190, v191
	v_cvt_pk_bf16_f32 v123, v192, v193
	v_cvt_pk_bf16_f32 v124, v194, v195
	v_cvt_pk_bf16_f32 v125, v196, v197
	v_lshl_add_u64 v[250:251], v[168:169], 0, v[248:249]
	global_load_dwordx4 v[190:193], v[250:251], off offset:128
	global_load_dwordx4 v[194:197], v[250:251], off offset:144
	v_mfma_f32_16x16x32_bf16 v[82:85], v[122:125], v[110:113], v[82:85]
	v_mfma_f32_16x16x32_bf16 v[58:61], v[122:125], v[114:117], v[58:61]
	v_mfma_f32_16x16x32_bf16 v[30:33], v[122:125], v[118:121], v[30:33]
	s_waitcnt vmcnt(20)
	v_cvt_pk_bf16_f32 v122, v198, v199
	v_cvt_pk_bf16_f32 v123, v200, v201
	v_cvt_pk_bf16_f32 v124, v202, v203
	v_cvt_pk_bf16_f32 v125, v204, v205
	v_lshl_add_u64 v[250:251], v[172:173], 0, v[248:249]
	global_load_dwordx4 v[198:201], v[250:251], off offset:128
	global_load_dwordx4 v[202:205], v[250:251], off offset:144
	v_mfma_f32_16x16x32_bf16 v[86:89], v[122:125], v[110:113], v[86:89]
	v_mfma_f32_16x16x32_bf16 v[54:57], v[122:125], v[114:117], v[54:57]
	v_mfma_f32_16x16x32_bf16 v[26:29], v[122:125], v[118:121], v[26:29]
	s_waitcnt vmcnt(20)
	v_cvt_pk_bf16_f32 v122, v206, v207
	v_cvt_pk_bf16_f32 v123, v208, v209
	v_cvt_pk_bf16_f32 v124, v210, v211
	v_cvt_pk_bf16_f32 v125, v212, v213
	v_lshl_add_u64 v[250:251], v[174:175], 0, v[248:249]
	global_load_dwordx4 v[206:209], v[250:251], off offset:128
	global_load_dwordx4 v[210:213], v[250:251], off offset:144
	v_mfma_f32_16x16x32_bf16 v[94:97], v[122:125], v[110:113], v[94:97]
	v_mfma_f32_16x16x32_bf16 v[62:65], v[122:125], v[114:117], v[62:65]
	v_mfma_f32_16x16x32_bf16 v[34:37], v[122:125], v[118:121], v[34:37]
	s_waitcnt vmcnt(12)
	v_cvt_pk_bf16_f32 v122, v126, v127
	v_cvt_pk_bf16_f32 v123, v128, v129
	v_cvt_pk_bf16_f32 v124, v138, v139
	v_cvt_pk_bf16_f32 v125, v140, v141
	v_lshl_add_u64 v[250:251], v[176:177], 0, v[248:249]
	global_load_dwordx4 v[126:129], v[250:251], off offset:128
	global_load_dwordx4 v[138:141], v[250:251], off offset:144
	v_mfma_f32_16x16x32_bf16 v[98:101], v[122:125], v[110:113], v[98:101]
	v_mfma_f32_16x16x32_bf16 v[74:77], v[122:125], v[114:117], v[74:77]
	v_mfma_f32_16x16x32_bf16 v[42:45], v[122:125], v[118:121], v[42:45]
	s_waitcnt vmcnt(12)
	v_cvt_pk_bf16_f32 v122, v142, v143
	v_cvt_pk_bf16_f32 v123, v144, v145
	v_cvt_pk_bf16_f32 v124, v146, v147
	v_cvt_pk_bf16_f32 v125, v148, v149
	v_lshl_add_u64 v[250:251], v[178:179], 0, v[248:249]
	global_load_dwordx4 v[142:145], v[250:251], off offset:128
	global_load_dwordx4 v[146:149], v[250:251], off offset:144
	v_mfma_f32_16x16x32_bf16 v[106:109], v[122:125], v[110:113], v[106:109]
	v_mfma_f32_16x16x32_bf16 v[102:105], v[122:125], v[114:117], v[102:105]
	v_mfma_f32_16x16x32_bf16 v[90:93], v[122:125], v[118:121], v[90:93]
	v_cvt_pk_bf16_f32 v110, v158, v214
	v_cvt_pk_bf16_f32 v111, v218, v228
	v_cvt_pk_bf16_f32 v112, v232, v236
	v_cvt_pk_bf16_f32 v113, v240, v244
	v_cvt_pk_bf16_f32 v114, v159, v215
	v_cvt_pk_bf16_f32 v115, v219, v229
	v_cvt_pk_bf16_f32 v116, v233, v237
	v_cvt_pk_bf16_f32 v117, v241, v245
	v_cvt_pk_bf16_f32 v118, v160, v216
	v_cvt_pk_bf16_f32 v119, v220, v230
	v_cvt_pk_bf16_f32 v120, v234, v238
	v_cvt_pk_bf16_f32 v121, v242, v246
	s_waitcnt vmcnt(12)
	v_cvt_pk_bf16_f32 v122, v150, v151
	v_cvt_pk_bf16_f32 v123, v152, v153
	v_cvt_pk_bf16_f32 v124, v154, v155
	v_cvt_pk_bf16_f32 v125, v156, v157
	v_lshl_add_u64 v[250:251], v[180:181], 0, v[248:249]
	global_load_dwordx4 v[150:153], v[250:251], off offset:128
	global_load_dwordx4 v[154:157], v[250:251], off offset:144
	v_mfma_f32_16x16x32_bf16 v[18:21], v[122:125], v[110:113], v[18:21]
	v_mfma_f32_16x16x32_bf16 v[6:9], v[122:125], v[114:117], v[6:9]
	v_mfma_f32_16x16x32_bf16 v[2:5], v[122:125], v[118:121], v[2:5]
	s_waitcnt vmcnt(12)
	v_cvt_pk_bf16_f32 v122, v182, v183
	v_cvt_pk_bf16_f32 v123, v184, v185
	v_cvt_pk_bf16_f32 v124, v186, v187
	v_cvt_pk_bf16_f32 v125, v188, v189
	v_lshl_add_u64 v[250:251], v[166:167], 0, v[248:249]
	global_load_dwordx4 v[182:185], v[250:251], off offset:128
	global_load_dwordx4 v[186:189], v[250:251], off offset:144
	v_mfma_f32_16x16x32_bf16 v[70:73], v[122:125], v[110:113], v[70:73]
	v_mfma_f32_16x16x32_bf16 v[46:49], v[122:125], v[114:117], v[46:49]
	v_mfma_f32_16x16x32_bf16 v[10:13], v[122:125], v[118:121], v[10:13]
	s_waitcnt vmcnt(12)
	v_cvt_pk_bf16_f32 v122, v190, v191
	v_cvt_pk_bf16_f32 v123, v192, v193
	v_cvt_pk_bf16_f32 v124, v194, v195
	v_cvt_pk_bf16_f32 v125, v196, v197
	s_nop 1
	v_mfma_f32_16x16x32_bf16 v[66:69], v[122:125], v[110:113], v[66:69]
	v_mfma_f32_16x16x32_bf16 v[38:41], v[122:125], v[114:117], v[38:41]
	v_mfma_f32_16x16x32_bf16 v[14:17], v[122:125], v[118:121], v[14:17]
	s_waitcnt vmcnt(10)
	v_cvt_pk_bf16_f32 v122, v198, v199
	v_cvt_pk_bf16_f32 v123, v200, v201
	v_cvt_pk_bf16_f32 v124, v202, v203
	v_cvt_pk_bf16_f32 v125, v204, v205
	s_nop 1
	v_mfma_f32_16x16x32_bf16 v[78:81], v[122:125], v[110:113], v[78:81]
	v_mfma_f32_16x16x32_bf16 v[50:53], v[122:125], v[114:117], v[50:53]
	v_mfma_f32_16x16x32_bf16 v[22:25], v[122:125], v[118:121], v[22:25]
	s_waitcnt vmcnt(8)
	v_cvt_pk_bf16_f32 v122, v206, v207
	v_cvt_pk_bf16_f32 v123, v208, v209
	v_cvt_pk_bf16_f32 v124, v210, v211
	v_cvt_pk_bf16_f32 v125, v212, v213
	s_nop 1
	v_mfma_f32_16x16x32_bf16 v[82:85], v[122:125], v[110:113], v[82:85]
	v_mfma_f32_16x16x32_bf16 v[58:61], v[122:125], v[114:117], v[58:61]
	v_mfma_f32_16x16x32_bf16 v[30:33], v[122:125], v[118:121], v[30:33]
	s_waitcnt vmcnt(6)
	v_cvt_pk_bf16_f32 v122, v126, v127
	v_cvt_pk_bf16_f32 v123, v128, v129
	v_cvt_pk_bf16_f32 v124, v138, v139
	v_cvt_pk_bf16_f32 v125, v140, v141
	s_nop 1
	v_mfma_f32_16x16x32_bf16 v[86:89], v[122:125], v[110:113], v[86:89]
	v_mfma_f32_16x16x32_bf16 v[54:57], v[122:125], v[114:117], v[54:57]
	v_mfma_f32_16x16x32_bf16 v[26:29], v[122:125], v[118:121], v[26:29]
	s_waitcnt vmcnt(4)
	v_cvt_pk_bf16_f32 v122, v142, v143
	v_cvt_pk_bf16_f32 v123, v144, v145
	v_cvt_pk_bf16_f32 v124, v146, v147
	v_cvt_pk_bf16_f32 v125, v148, v149
	s_nop 1
	v_mfma_f32_16x16x32_bf16 v[94:97], v[122:125], v[110:113], v[94:97]
	v_mfma_f32_16x16x32_bf16 v[62:65], v[122:125], v[114:117], v[62:65]
	v_mfma_f32_16x16x32_bf16 v[34:37], v[122:125], v[118:121], v[34:37]
	s_waitcnt vmcnt(2)
	v_cvt_pk_bf16_f32 v122, v150, v151
	v_cvt_pk_bf16_f32 v123, v152, v153
	v_cvt_pk_bf16_f32 v124, v154, v155
	v_cvt_pk_bf16_f32 v125, v156, v157
	s_nop 1
	v_mfma_f32_16x16x32_bf16 v[98:101], v[122:125], v[110:113], v[98:101]
	v_mfma_f32_16x16x32_bf16 v[74:77], v[122:125], v[114:117], v[74:77]
	v_mfma_f32_16x16x32_bf16 v[42:45], v[122:125], v[118:121], v[42:45]
	s_waitcnt vmcnt(0)
	v_cvt_pk_bf16_f32 v122, v182, v183
	v_cvt_pk_bf16_f32 v123, v184, v185
	v_cvt_pk_bf16_f32 v124, v186, v187
	v_cvt_pk_bf16_f32 v125, v188, v189
	s_nop 1
	v_mfma_f32_16x16x32_bf16 v[106:109], v[122:125], v[110:113], v[106:109]
	v_mfma_f32_16x16x32_bf16 v[102:105], v[122:125], v[114:117], v[102:105]
	v_mfma_f32_16x16x32_bf16 v[90:93], v[122:125], v[118:121], v[90:93]
	s_cmpk_eq_i32 s63, 0x100
	s_cbranch_scc0 .LBB0_82
	v_lshrrev_b32_e32 v110, 4, v170
	v_lshlrev_b32_e32 v111, 16, v110
	v_lshlrev_b32_e32 v112, 2, v110
	v_or_b32_e32 v112, 0x82, v112
	v_lshlrev_b32_e32 v113, 2, v110
	v_or_b32_e32 v113, 0x80, v113
	v_lshlrev_b32_e32 v114, 2, v110
	v_or_b32_e32 v114, 0x81, v114
	v_or_b32_e32 v132, 0x4000, v111
	v_or_b32_e32 v134, 0x8000, v111
	v_or_b32_e32 v136, 0xc000, v111
	v_or_b32_e32 v138, 0x40000, v111
	v_or_b32_e32 v140, 0x44000, v111
	v_or_b32_e32 v142, 0x48000, v111
	v_or_b32_e32 v144, 0x4c000, v111
	v_or_b32_e32 v146, 0x80000, v111
	v_or_b32_e32 v148, 0x84000, v111
	v_or_b32_e32 v150, 0x88000, v111
	v_or_b32_e32 v152, 0x8c000, v111
	v_or_b32_e32 v154, 0xc0000, v111
	v_or_b32_e32 v156, 0xc4000, v111
	v_or_b32_e32 v158, 0xc8000, v111
	v_or_b32_e32 v160, 0xcc000, v111
	v_or_b32_e32 v182, 0x100000, v111
	v_or_b32_e32 v184, 0x104000, v111
	v_or_b32_e32 v186, 0x108000, v111
	v_or_b32_e32 v188, 0x10c000, v111
	v_or_b32_e32 v190, 0x140000, v111
	v_or_b32_e32 v192, 0x144000, v111
	v_or_b32_e32 v194, 0x148000, v111
	v_or_b32_e32 v196, 0x14c000, v111
	v_or_b32_e32 v198, 0x180000, v111
	v_or_b32_e32 v200, 0x184000, v111
	v_or_b32_e32 v202, 0x188000, v111
	v_or_b32_e32 v204, 0x18c000, v111
	v_or_b32_e32 v206, 0x1c0000, v111
	v_or_b32_e32 v208, 0x1c4000, v111
	v_or_b32_e32 v210, 0x1c8000, v111
	v_or_b32_e32 v212, 0x1cc000, v111
	v_lshlrev_b32_e32 v214, 2, v111
	v_add_u32_e32 v189, 0xffff7000, v137
	v_add_u32_e32 v191, 0xffff7100, v137
	v_add_u32_e32 v193, 0xffff7200, v137
	v_add_u32_e32 v195, 0xffff7300, v137
	v_add_u32_e32 v197, 0xffff7400, v137
	v_add_u32_e32 v199, 0xffff7500, v137
	v_add_u32_e32 v201, 0xffff7600, v137
	v_add_u32_e32 v203, 0xffff7700, v137
	v_add_u32_e32 v205, 0xffff7800, v137
	v_add_u32_e32 v207, 0xffff7900, v137
	v_add_u32_e32 v209, 0xffff7a00, v137
	v_add_u32_e32 v211, 0xffff7b00, v137
	v_add_u32_e32 v213, 0xffff7c00, v137
	v_add_u32_e32 v217, 0xffff7d00, v137
	v_add_u32_e32 v219, 0xffff7e00, v137
	v_add_u32_e32 v221, 0xffff7f00, v137
	v_add_u32_e32 v171, 0xffff8000, v137
	v_add_u32_e32 v247, 0xffff8100, v137
	v_add_u32_e32 v183, 0xffff8200, v137
	v_add_u32_e32 v185, 0xffff8300, v137
	v_add_u32_e32 v187, 0xffff8400, v137
	v_add_u32_e32 v251, 0xffff8500, v137
	v_add_u32_e32 v252, 0xffff8600, v137
	v_add_u32_e32 v253, 0xffff8700, v137
	v_add_u32_e32 v254, 0xffff8800, v137
	v_add_u32_e32 v139, 0xffff8900, v137
	v_add_u32_e32 v141, 0xffff8a00, v137
	v_add_u32_e32 v143, 0xffff8b00, v137
	v_add_u32_e32 v145, 0xffff8c00, v137
	v_add_u32_e32 v147, 0xffff8d00, v137
	v_add_u32_e32 v149, 0xffff8e00, v137
	v_add_u32_e32 v151, 0xffff8f00, v137
	v_add_u32_e32 v153, 0xffff9000, v137
	v_add_u32_e32 v155, 0xffff9100, v137
	v_add_u32_e32 v157, 0xffff9200, v137
	v_add_u32_e32 v159, 0xffff9300, v137
	v_lshlrev_b32_e32 v216, 14, v113
	v_lshlrev_b32_e32 v218, 14, v114
	v_lshlrev_b32_e32 v220, 14, v112
	s_and_b64 vcc, exec, s[10:11]
	s_cbranch_vccz .LBB0_85
	v_add_u32_e32 v110, 0xfffe5000, v137
	ds_write_b32 v110, v18
	v_add_u32_e32 v110, 0xfffe5100, v137
	ds_write_b32 v110, v19
	v_add_u32_e32 v110, 0xfffe5200, v137
	ds_write_b32 v110, v20
	v_add_u32_e32 v110, 0xfffe5300, v137
	ds_write_b32 v110, v21
	v_add_u32_e32 v110, 0xfffe5400, v137
	ds_write_b32 v110, v6
	v_add_u32_e32 v110, 0xfffe5500, v137
	ds_write_b32 v110, v7
	v_add_u32_e32 v110, 0xfffe5600, v137
	ds_write_b32 v110, v8
	v_add_u32_e32 v110, 0xfffe5700, v137
	ds_write_b32 v110, v9
	v_add_u32_e32 v110, 0xfffe5800, v137
	ds_write_b32 v110, v2
	v_add_u32_e32 v110, 0xfffe5900, v137
	ds_write_b32 v110, v3
	v_add_u32_e32 v110, 0xfffe5a00, v137
	ds_write_b32 v110, v4
	v_add_u32_e32 v110, 0xfffe5b00, v137
	ds_write_b32 v110, v5
	v_add_u32_e32 v110, 0xfffe5c00, v137
	ds_write_b32 v110, v70
	v_add_u32_e32 v110, 0xfffe5d00, v137
	ds_write_b32 v110, v71
	v_add_u32_e32 v110, 0xfffe5e00, v137
	ds_write_b32 v110, v72
	v_add_u32_e32 v110, 0xfffe5f00, v137
	ds_write_b32 v110, v73
	v_add_u32_e32 v110, 0xfffe6000, v137
	ds_write_b32 v110, v46
	v_add_u32_e32 v110, 0xfffe6100, v137
	ds_write_b32 v110, v47
	v_add_u32_e32 v110, 0xfffe6200, v137
	ds_write_b32 v110, v48
	v_add_u32_e32 v110, 0xfffe6300, v137
	ds_write_b32 v110, v49
	v_add_u32_e32 v110, 0xfffe6400, v137
	ds_write_b32 v110, v10
	v_add_u32_e32 v110, 0xfffe6500, v137
	ds_write_b32 v110, v11
	v_add_u32_e32 v110, 0xfffe6600, v137
	ds_write_b32 v110, v12
	v_add_u32_e32 v110, 0xfffe6700, v137
	ds_write_b32 v110, v13
	v_add_u32_e32 v110, 0xfffe6800, v137
	ds_write_b32 v110, v66
	v_add_u32_e32 v110, 0xfffe6900, v137
	ds_write_b32 v110, v67
	v_add_u32_e32 v110, 0xfffe6a00, v137
	ds_write_b32 v110, v68
	v_add_u32_e32 v110, 0xfffe6b00, v137
	ds_write_b32 v110, v69
	v_add_u32_e32 v110, 0xfffe6c00, v137
	ds_write_b32 v110, v38
	v_add_u32_e32 v110, 0xfffe6d00, v137
	ds_write_b32 v110, v39
	v_add_u32_e32 v110, 0xfffe6e00, v137
	ds_write_b32 v110, v40
	v_add_u32_e32 v110, 0xfffe6f00, v137
	ds_write_b32 v110, v41
	v_add_u32_e32 v110, 0xfffe7000, v137
	ds_write_b32 v110, v14
	v_add_u32_e32 v110, 0xfffe7100, v137
	ds_write_b32 v110, v15
	v_add_u32_e32 v110, 0xfffe7200, v137
	ds_write_b32 v110, v16
	v_add_u32_e32 v110, 0xfffe7300, v137
	ds_write_b32 v110, v17
	v_add_u32_e32 v110, 0xfffe7400, v137
	ds_write_b32 v110, v78
	v_add_u32_e32 v110, 0xfffe7500, v137
	ds_write_b32 v110, v79
	v_add_u32_e32 v110, 0xfffe7600, v137
	ds_write_b32 v110, v80
	v_add_u32_e32 v110, 0xfffe7700, v137
	ds_write_b32 v110, v81
	v_add_u32_e32 v110, 0xfffe7800, v137
	ds_write_b32 v110, v50
	v_add_u32_e32 v110, 0xfffe7900, v137
	ds_write_b32 v110, v51
	v_add_u32_e32 v110, 0xfffe7a00, v137
	ds_write_b32 v110, v52
	v_add_u32_e32 v110, 0xfffe7b00, v137
	ds_write_b32 v110, v53
	v_add_u32_e32 v110, 0xfffe7c00, v137
	ds_write_b32 v110, v22
	v_add_u32_e32 v110, 0xfffe7d00, v137
	ds_write_b32 v110, v23
	v_add_u32_e32 v110, 0xfffe7e00, v137
	ds_write_b32 v110, v24
	v_add_u32_e32 v110, 0xfffe7f00, v137
	ds_write_b32 v110, v25
	v_add_u32_e32 v110, 0xfffe8000, v137
	ds_write_b32 v110, v82
	v_add_u32_e32 v110, 0xfffe8100, v137
	ds_write_b32 v110, v83
	v_add_u32_e32 v110, 0xfffe8200, v137
	ds_write_b32 v110, v84
	v_add_u32_e32 v110, 0xfffe8300, v137
	ds_write_b32 v110, v85
	v_add_u32_e32 v110, 0xfffe8400, v137
	ds_write_b32 v110, v58
	v_add_u32_e32 v110, 0xfffe8500, v137
	ds_write_b32 v110, v59
	v_add_u32_e32 v110, 0xfffe8600, v137
	ds_write_b32 v110, v60
	v_add_u32_e32 v110, 0xfffe8700, v137
	ds_write_b32 v110, v61
	v_add_u32_e32 v110, 0xfffe8800, v137
	ds_write_b32 v110, v30
	v_add_u32_e32 v110, 0xfffe8900, v137
	ds_write_b32 v110, v31
	v_add_u32_e32 v110, 0xfffe8a00, v137
	ds_write_b32 v110, v32
	v_add_u32_e32 v110, 0xfffe8b00, v137
	ds_write_b32 v110, v33
	v_add_u32_e32 v110, 0xfffe8c00, v137
	ds_write_b32 v110, v86
	v_add_u32_e32 v110, 0xfffe8d00, v137
	ds_write_b32 v110, v87
	v_add_u32_e32 v110, 0xfffe8e00, v137
	ds_write_b32 v110, v88
	v_add_u32_e32 v110, 0xfffe8f00, v137
	ds_write_b32 v110, v89
	v_add_u32_e32 v110, 0xfffe9000, v137
	ds_write_b32 v110, v54
	v_add_u32_e32 v110, 0xfffe9100, v137
	ds_write_b32 v110, v55
	v_add_u32_e32 v110, 0xfffe9200, v137
	ds_write_b32 v110, v56
	v_add_u32_e32 v110, 0xfffe9300, v137
	ds_write_b32 v110, v57
	v_add_u32_e32 v110, 0xfffe9400, v137
	ds_write_b32 v110, v26
	v_add_u32_e32 v110, 0xfffe9500, v137
	ds_write_b32 v110, v27
	v_add_u32_e32 v110, 0xfffe9600, v137
	ds_write_b32 v110, v28
	v_add_u32_e32 v110, 0xfffe9700, v137
	ds_write_b32 v110, v29
	v_add_u32_e32 v110, 0xfffe9800, v137
	ds_write_b32 v110, v94
	v_add_u32_e32 v110, 0xfffe9900, v137
	ds_write_b32 v110, v95
	v_add_u32_e32 v110, 0xfffe9a00, v137
	ds_write_b32 v110, v96
	v_add_u32_e32 v110, 0xfffe9b00, v137
	ds_write_b32 v110, v97
	v_add_u32_e32 v110, 0xfffe9c00, v137
	ds_write_b32 v110, v62
	v_add_u32_e32 v110, 0xfffe9d00, v137
	ds_write_b32 v110, v63
	v_add_u32_e32 v110, 0xfffe9e00, v137
	ds_write_b32 v110, v64
	v_add_u32_e32 v110, 0xfffe9f00, v137
	ds_write_b32 v110, v65
	v_add_u32_e32 v110, 0xfffea000, v137
	ds_write_b32 v110, v34
	v_add_u32_e32 v110, 0xfffea100, v137
	ds_write_b32 v110, v35
	v_add_u32_e32 v110, 0xfffea200, v137
	ds_write_b32 v110, v36
	v_add_u32_e32 v110, 0xfffea300, v137
	ds_write_b32 v110, v37
	v_add_u32_e32 v110, 0xfffea400, v137
	ds_write_b32 v110, v98
	v_add_u32_e32 v110, 0xfffea500, v137
	ds_write_b32 v110, v99
	v_add_u32_e32 v110, 0xfffea600, v137
	ds_write_b32 v110, v100
	v_add_u32_e32 v110, 0xfffea700, v137
	ds_write_b32 v110, v101
	v_add_u32_e32 v110, 0xfffea800, v137
	ds_write_b32 v110, v74
	v_add_u32_e32 v110, 0xfffea900, v137
	ds_write_b32 v110, v75
	v_add_u32_e32 v110, 0xfffeaa00, v137
	ds_write_b32 v110, v76
	v_add_u32_e32 v110, 0xfffeab00, v137
	ds_write_b32 v110, v77
	v_add_u32_e32 v110, 0xfffeac00, v137
	ds_write_b32 v110, v42
	v_add_u32_e32 v110, 0xfffead00, v137
	ds_write_b32 v110, v43
	v_add_u32_e32 v110, 0xfffeae00, v137
	ds_write_b32 v110, v44
	v_add_u32_e32 v110, 0xfffeaf00, v137
	ds_write_b32 v110, v45
	v_add_u32_e32 v110, 0xfffeb000, v137
	ds_write_b32 v110, v106
	v_add_u32_e32 v110, 0xfffeb100, v137
	ds_write_b32 v110, v107
	v_add_u32_e32 v110, 0xfffeb200, v137
	ds_write_b32 v110, v108
	v_add_u32_e32 v110, 0xfffeb300, v137
	ds_write_b32 v110, v109
	v_add_u32_e32 v110, 0xfffeb400, v137
	ds_write_b32 v110, v102
	v_add_u32_e32 v110, 0xfffeb500, v137
	ds_write_b32 v110, v103
	v_add_u32_e32 v110, 0xfffeb600, v137
	ds_write_b32 v110, v104
	v_add_u32_e32 v110, 0xfffeb700, v137
	ds_write_b32 v110, v105
	v_add_u32_e32 v110, 0xfffeb800, v137
	ds_write_b32 v110, v90
	v_add_u32_e32 v110, 0xfffeb900, v137
	ds_write_b32 v110, v91
	v_add_u32_e32 v110, 0xfffeba00, v137
	ds_write_b32 v110, v92
	v_add_u32_e32 v110, 0xfffebb00, v137
	ds_write_b32 v110, v93
